# GEMM stream prologues: serializing wait between the two load batches dropped (on top of the P3 prefetch)
# baseline (speedup 1.0000x reference)
.LBB0_190:
	s_lshl_b32 s14, s14, 12
	s_lshl_b32 s21, s15, 13
	s_and_b32 s22, s14, 0x3000
	s_mov_b64 s[14:15], 0x80
	s_add_i32 s61, s5, 0x18000
	v_lshl_add_u64 v[0:1], v[0:1], 0, s[14:15]
	s_mov_b32 m0, s61
	s_add_i32 s62, s5, 0x1a000
	s_barrier
	global_load_lds_dwordx4 v[0:1], off
	v_lshl_add_u64 v[0:1], v[2:3], 0, s[14:15]
	s_mov_b32 m0, s62
	s_add_i32 s63, s5, 0x8000
	s_add_i32 s64, s5, 0xa000
	global_load_lds_dwordx4 v[0:1], off
	v_lshl_add_u64 v[0:1], v[6:7], 0, s[14:15]
	s_mov_b32 m0, s63
	s_add_u32 s16, s52, 0x40080
	global_load_lds_dwordx4 v[0:1], off
	v_lshl_add_u64 v[0:1], v[4:5], 0, s[14:15]
	s_mov_b32 m0, s64
	s_addc_u32 s17, s53, 0
	s_add_i32 s65, s5, 0x1c000
	global_load_lds_dwordx4 v[0:1], off
	v_lshl_add_u64 v[0:1], v[72:73], 1, s[16:17]
	s_mov_b32 m0, s65
	s_add_i32 s67, s5, 0x1e000
	global_load_lds_dwordx4 v[0:1], off
	v_lshl_add_u64 v[0:1], v[74:75], 1, s[16:17]
	s_mov_b32 m0, s67
	v_and_b32_e32 v2, 3, v10
	global_load_lds_dwordx4 v[0:1], off
	v_lshlrev_b32_e32 v0, 1, v150
	v_lshrrev_b32_e32 v1, 2, v150
	s_movk_i32 s16, 0xffe0
	v_and_b32_e32 v0, 24, v0
	v_and_b32_e32 v1, 4, v1
	v_and_or_b32 v2, v150, s16, v2
	v_or3_b32 v154, v2, v0, v1
	v_lshlrev_b32_e32 v0, 1, v152
	v_lshrrev_b32_e32 v1, 2, v152
	v_and_b32_e32 v2, 3, v14
	v_and_b32_e32 v0, 24, v0
	v_and_b32_e32 v1, 4, v1
	v_and_or_b32 v2, v152, s16, v2
	v_or3_b32 v155, v2, v0, v1
	v_and_b32_e32 v0, 15, v8
	v_lshlrev_b32_e32 v3, 2, v8
	v_and_b32_e32 v1, 48, v8
	v_lshlrev_b32_e32 v0, 6, v0
	v_and_b32_e32 v3, 32, v3
	v_or_b32_e32 v2, v0, v1
	v_bitop3_b32 v0, v0, v3, v1 bitop3:0x36
	v_or_b32_e32 v5, s22, v0
	v_lshlrev_b32_e32 v0, 13, v9
	v_and_b32_e32 v0, 0xffffc000, v0
	v_lshl_add_u32 v0, v10, 10, v0
	v_or_b32_e32 v0, v0, v11
	v_add_u32_sdwa v0, v0, sext(v13) dst_sel:DWORD dst_unused:UNUSED_PAD src0_sel:DWORD src1_sel:WORD_0
	v_bitop3_b32 v4, v2, s21, v3 bitop3:0xde
	v_ashrrev_i32_e32 v1, 31, v0
	v_mov_b64_e32 v[2:3], 0x40080
	v_lshl_add_u64 v[140:141], v[0:1], 1, v[2:3]
	v_lshlrev_b32_e32 v0, 13, v12
	v_and_b32_e32 v0, 0xffffc000, v0
	v_lshl_add_u32 v0, v14, 10, v0
	v_or_b32_e32 v0, v0, v15
	s_ashr_i32 s68, s28, 31
	s_ashr_i32 s70, s2, 31
	s_ashr_i32 s71, s2, 3
	s_ashr_i32 s72, s28, 3
	s_and_b32 s73, s2, 7
	v_add_u32_sdwa v0, v0, sext(v16) dst_sel:DWORD dst_unused:UNUSED_PAD src0_sel:DWORD src1_sel:WORD_0
	s_waitcnt vmcnt(6)
	s_cmpk_lt_u32 s20, 0x100
	v_ashrrev_i32_e32 v1, 31, v0
	s_cselect_b64 s[16:17], -1, 0
	s_add_u32 s74, s26, 0x1e7e5000
	v_lshl_add_u64 v[142:143], v[0:1], 1, v[2:3]
	v_add_u32_e32 v0, 0, v5
	s_mov_b32 s69, s28
	s_addc_u32 s75, s27, 0
	v_add_u32_e32 v156, 0x10000, v0
	v_add_u32_e32 v157, 0x14000, v0
	v_add_u32_e32 v158, 0, v4
	s_add_i32 s76, s5, 0xc000
	s_add_i32 s77, s5, 0xe000
	v_add_u32_e32 v159, 0x18000, v0
	v_add_u32_e32 v160, 0x1c000, v0
	s_mov_b32 s78, 0x16300000
	s_movk_i32 s79, 0xee00
	v_mov_b32_e32 v145, 0
	v_mov_b64_e32 v[146:147], 0x5ff
	s_mov_b32 s80, 0
	s_barrier
	s_branch .LBB0_193

.LBB0_233:
	s_mov_b64 s[0:1], 0x80
	v_lshl_add_u64 v[4:5], v[4:5], 0, s[0:1]
	s_add_i32 m0, s18, 0x18000
	s_barrier
	global_load_lds_dwordx4 v[4:5], off
	v_lshl_add_u64 v[4:5], v[6:7], 0, s[0:1]
	s_add_i32 m0, s18, 0x1a000
	s_nop 0
	global_load_lds_dwordx4 v[4:5], off
	v_lshl_add_u64 v[4:5], v[8:9], 0, s[0:1]
	s_add_i32 m0, s18, 0x8000
	s_nop 0
	global_load_lds_dwordx4 v[4:5], off
	s_add_i32 m0, s18, 0xa000
	v_lshl_add_u64 v[4:5], v[10:11], 0, s[0:1]
	s_add_u32 s0, s58, 0x40080
	s_addc_u32 s1, s59, 0
	global_load_lds_dwordx4 v[4:5], off
	v_lshl_add_u64 v[4:5], v[96:97], 1, s[0:1]
	s_add_i32 m0, s18, 0x1c000
	s_nop 0
	global_load_lds_dwordx4 v[4:5], off
	v_lshl_add_u64 v[4:5], v[98:99], 1, s[0:1]
	s_add_i32 m0, s18, 0x1e000
	s_nop 0
	global_load_lds_dwordx4 v[4:5], off
	s_waitcnt vmcnt(6)
	s_barrier
	s_branch .LBB0_238

.LBB0_343:
	s_mov_b64 s[14:15], 0x80
	v_lshl_add_u64 v[4:5], v[4:5], 0, s[14:15]
	s_add_i32 m0, s67, 0x18000
	s_barrier
	global_load_lds_dwordx4 v[4:5], off
	v_lshl_add_u64 v[4:5], v[6:7], 0, s[14:15]
	s_add_i32 m0, s67, 0x1a000
	s_nop 0
	global_load_lds_dwordx4 v[4:5], off
	v_lshl_add_u64 v[4:5], v[10:11], 0, s[14:15]
	s_add_i32 m0, s67, 0x8000
	s_nop 0
	global_load_lds_dwordx4 v[4:5], off
	s_add_i32 m0, s67, 0xa000
	v_lshl_add_u64 v[4:5], v[8:9], 0, s[14:15]
	s_add_u32 s14, s56, 0x40080
	s_addc_u32 s15, s57, 0
	global_load_lds_dwordx4 v[4:5], off
	v_lshl_add_u64 v[4:5], v[0:1], 1, s[14:15]
	s_add_i32 m0, s67, 0x1c000
	s_nop 0
	global_load_lds_dwordx4 v[4:5], off
	v_lshl_add_u64 v[4:5], v[2:3], 1, s[14:15]
	s_add_i32 m0, s67, 0x1e000
	s_nop 0
	global_load_lds_dwordx4 v[4:5], off
	s_waitcnt vmcnt(6)
	s_barrier
	s_branch .LBB0_348

.LBB0_412:
	s_mov_b64 s[0:1], 0x80
	v_lshl_add_u64 v[4:5], v[4:5], 0, s[0:1]
	s_add_i32 m0, s18, 0x18000
	s_barrier
	global_load_lds_dwordx4 v[4:5], off
	v_lshl_add_u64 v[4:5], v[6:7], 0, s[0:1]
	s_add_i32 m0, s18, 0x1a000
	s_nop 0
	global_load_lds_dwordx4 v[4:5], off
	v_lshl_add_u64 v[4:5], v[10:11], 0, s[0:1]
	s_add_i32 m0, s18, 0x8000
	s_nop 0
	global_load_lds_dwordx4 v[4:5], off
	s_add_i32 m0, s18, 0xa000
	v_lshl_add_u64 v[4:5], v[8:9], 0, s[0:1]
	s_add_u32 s0, s48, 0x40080
	s_addc_u32 s1, s49, 0
	global_load_lds_dwordx4 v[4:5], off
	v_lshl_add_u64 v[4:5], v[0:1], 1, s[0:1]
	s_add_i32 m0, s18, 0x1c000
	s_nop 0
	global_load_lds_dwordx4 v[4:5], off
	v_lshl_add_u64 v[4:5], v[2:3], 1, s[0:1]
	s_add_i32 m0, s18, 0x1e000
	s_nop 0
	global_load_lds_dwordx4 v[4:5], off
	s_waitcnt vmcnt(6)
	s_barrier
	s_branch .LBB0_418

.LBB0_820:
	s_add_u32 s8, s26, 0x1a300000
	s_addc_u32 s9, s27, 0
	s_lshl_b32 s6, s6, 12
	s_lshl_b32 s13, s7, 13
	s_and_b32 s14, s6, 0x3000
	s_mov_b64 s[10:11], 0x80
	s_add_i32 s72, s18, 0x18000
	s_add_i32 s73, s18, 0x1a000
	v_lshl_add_u64 v[0:1], v[0:1], 0, s[10:11]
	s_mov_b32 m0, s72
	s_add_u32 s6, s48, 0x100000
	s_barrier
	global_load_lds_dwordx4 v[0:1], off
	v_lshl_add_u64 v[0:1], v[2:3], 0, s[10:11]
	s_mov_b32 m0, s73
	s_addc_u32 s7, s49, 0
	s_add_i32 s74, s18, 0x8000
	global_load_lds_dwordx4 v[0:1], off
	v_lshl_add_u64 v[0:1], v[130:131], 1, s[6:7]
	s_mov_b32 m0, s74
	s_add_i32 s76, s18, 0xa000
	global_load_lds_dwordx4 v[0:1], off
	v_lshl_add_u64 v[0:1], v[128:129], 1, s[6:7]
	s_add_u32 s6, s54, 0x20080
	s_mov_b32 m0, s76
	s_addc_u32 s7, s55, 0
	s_add_i32 s77, s18, 0x1c000
	global_load_lds_dwordx4 v[0:1], off
	v_lshl_add_u64 v[0:1], v[132:133], 1, s[6:7]
	s_mov_b32 m0, s77
	s_add_i32 s78, s18, 0x1e000
	global_load_lds_dwordx4 v[0:1], off
	v_lshl_add_u64 v[0:1], v[134:135], 1, s[6:7]
	s_mov_b32 m0, s78
	v_lshlrev_b32_e32 v3, 2, v4
	global_load_lds_dwordx4 v[0:1], off
	v_and_b32_e32 v0, 15, v4
	v_and_b32_e32 v1, 48, v4
	v_lshlrev_b32_e32 v0, 6, v0
	v_and_b32_e32 v3, 32, v3
	s_ashr_i32 s79, s2, 31
	s_ashr_i32 s80, s2, 3
	s_ashr_i32 s81, s28, 3
	s_and_b32 s82, s2, 7
	v_or_b32_e32 v2, v0, v1
	v_bitop3_b32 v0, v0, v3, v1 bitop3:0x36
	s_waitcnt vmcnt(6)
	s_cmpk_lt_u32 s12, 0x100
	v_bitop3_b32 v1, v2, s13, v3 bitop3:0xde
	v_or_b32_e32 v0, s14, v0
	s_cselect_b64 s[12:13], -1, 0
	s_add_u32 s83, s26, 0x10300000
	s_addc_u32 s84, s27, 0
	s_mov_b32 s58, 64
	s_movk_i32 s91, 0x200
	s_mov_b64 s[6:7], 0x80000
	v_add_u32_e32 v199, 0, v0
	v_add_u32_e32 v222, 0, v1
	s_add_i32 s85, s18, 0xc000
	s_add_i32 s86, s18, 0xe000
	v_mov_b32_e32 v201, 0
	v_mov_b64_e32 v[202:203], 0x1ff
	s_barrier
	s_branch .LBB0_823

.LBB0_944:
	s_mov_b64 s[10:11], 0x80
	s_add_i32 s87, s30, 0x18000
	s_lshl_b32 s1, s1, 12
	v_lshl_add_u64 v[4:5], v[4:5], 0, s[10:11]
	s_mov_b32 m0, s87
	s_add_i32 s88, s30, 0x1a000
	s_lshl_b32 s7, s7, 13
	s_and_b32 s1, s1, 0x3000
	s_barrier
	global_load_lds_dwordx4 v[4:5], off
	v_lshl_add_u64 v[4:5], v[6:7], 0, s[10:11]
	s_mov_b32 m0, s88
	s_add_i32 s89, s30, 0x8000
	s_add_i32 s90, s30, 0xa000
	global_load_lds_dwordx4 v[4:5], off
	v_lshl_add_u64 v[4:5], v[10:11], 0, s[10:11]
	s_mov_b32 m0, s89
	s_add_u32 s14, s64, 0x40080
	global_load_lds_dwordx4 v[4:5], off
	v_lshl_add_u64 v[4:5], v[8:9], 0, s[10:11]
	s_mov_b32 m0, s90
	s_addc_u32 s15, s65, 0
	s_add_i32 s91, s30, 0x1c000
	global_load_lds_dwordx4 v[4:5], off
	v_lshl_add_u64 v[2:3], v[2:3], 1, s[14:15]
	s_mov_b32 m0, s91
	s_add_i32 s92, s30, 0x1e000
	global_load_lds_dwordx4 v[2:3], off
	v_lshl_add_u64 v[0:1], v[0:1], 1, s[14:15]
	s_mov_b32 m0, s92
	v_lshlrev_b32_e32 v3, 2, v12
	global_load_lds_dwordx4 v[0:1], off
	v_and_b32_e32 v0, 15, v12
	v_and_b32_e32 v1, 48, v12
	v_lshlrev_b32_e32 v0, 6, v0
	v_and_b32_e32 v3, 32, v3
	v_or_b32_e32 v2, v0, v1
	v_bitop3_b32 v0, v0, v3, v1 bitop3:0x36
	v_or_b32_e32 v5, s1, v0
	v_lshlrev_b32_e32 v0, 13, v13
	v_and_b32_e32 v0, 0xffffc000, v0
	v_lshl_add_u32 v0, v14, 10, v0
	v_or_b32_e32 v0, v0, v15
	v_add_u32_sdwa v0, v0, sext(v17) dst_sel:DWORD dst_unused:UNUSED_PAD src0_sel:DWORD src1_sel:WORD_0
	v_bitop3_b32 v4, v2, s7, v3 bitop3:0xde
	v_ashrrev_i32_e32 v1, 31, v0
	v_mov_b64_e32 v[2:3], 0x40080
	v_lshl_add_u64 v[180:181], v[0:1], 1, v[2:3]
	v_lshlrev_b32_e32 v0, 13, v16
	v_and_b32_e32 v0, 0xffffc000, v0
	v_lshl_add_u32 v0, v18, 10, v0
	v_or_b32_e32 v0, v0, v19
	v_add_u32_sdwa v0, v0, sext(v20) dst_sel:DWORD dst_unused:UNUSED_PAD src0_sel:DWORD src1_sel:WORD_0
	s_ashr_i32 s93, s28, 31
	s_ashr_i32 s95, s2, 31
	s_ashr_i32 s96, s2, 3
	s_ashr_i32 s97, s28, 3
	s_and_b32 s74, s2, 7
	v_ashrrev_i32_e32 v1, 31, v0
	s_waitcnt vmcnt(6)
	s_cmpk_lt_u32 s12, 0x100
	v_lshl_add_u64 v[182:183], v[0:1], 1, v[2:3]
	v_add_u32_e32 v0, 0, v5
	s_cselect_b64 s[12:13], -1, 0
	s_add_u32 s38, s26, 0x1e720000
	v_add_u32_e32 v195, 0x10000, v0
	v_add_u32_e32 v198, 0x14000, v0
	v_add_u32_e32 v200, 0x18000, v0
	v_add_u32_e32 v201, 0x1c000, v0
	v_mbcnt_lo_u32_b32 v0, -1, 0
	s_mov_b32 s94, s28
	s_addc_u32 s39, s27, 0
	v_add_u32_e32 v199, 0, v4
	s_add_i32 s78, s30, 0xc000
	s_add_i32 s31, s30, 0xe000
	v_mov_b32_e32 v185, 0
	s_mov_b64 s[14:15], 0x20000
	v_mbcnt_hi_u32_b32 v202, -1, v0
	s_mov_b64 s[16:17], 0x80000
	s_mov_b64 s[20:21], 0x80200
	s_mov_b64 s[40:41], 0x90000
	s_mov_b64 s[42:43], 0x90200
	s_mov_b64 s[44:45], 0xa0000
	s_mov_b64 s[46:47], 0xa0200
	s_mov_b64 s[48:49], 0xb0000
	s_mov_b64 s[50:51], 0xb0200
	s_mov_b64 s[52:53], 0x24000
	s_mov_b64 s[54:55], 0x28000
	s_mov_b64 s[56:57], 0x2c000
	v_mov_b64_e32 v[186:187], 0x1ff
	s_barrier
	s_branch .LBB0_947

.LBB0_1046:
	s_lshl_b32 s4, s4, 12
	s_lshl_b32 s7, s5, 13
	s_and_b32 s10, s4, 0x3000
	s_mov_b64 s[4:5], 0x80
	s_add_i32 s54, s3, 0x18000
	v_lshl_add_u64 v[4:5], v[4:5], 0, s[4:5]
	s_mov_b32 m0, s54
	s_add_i32 s55, s3, 0x1a000
	s_barrier
	global_load_lds_dwordx4 v[4:5], off
	v_lshl_add_u64 v[4:5], v[6:7], 0, s[4:5]
	s_mov_b32 m0, s55
	s_add_i32 s56, s3, 0x8000
	s_add_i32 s57, s3, 0xa000
	global_load_lds_dwordx4 v[4:5], off
	v_lshl_add_u64 v[4:5], v[10:11], 0, s[4:5]
	s_mov_b32 m0, s56
	s_add_u32 s8, s40, 0x40080
	global_load_lds_dwordx4 v[4:5], off
	v_lshl_add_u64 v[4:5], v[8:9], 0, s[4:5]
	s_mov_b32 m0, s57
	s_addc_u32 s9, s41, 0
	s_add_i32 s58, s3, 0x1c000
	global_load_lds_dwordx4 v[4:5], off
	v_lshl_add_u64 v[2:3], v[2:3], 1, s[8:9]
	s_mov_b32 m0, s58
	s_add_i32 s59, s3, 0x1e000
	global_load_lds_dwordx4 v[2:3], off
	v_lshl_add_u64 v[0:1], v[0:1], 1, s[8:9]
	s_mov_b32 m0, s59
	v_lshlrev_b32_e32 v3, 2, v12
	global_load_lds_dwordx4 v[0:1], off
	v_and_b32_e32 v0, 15, v12
	v_and_b32_e32 v1, 48, v12
	v_lshlrev_b32_e32 v0, 6, v0
	v_and_b32_e32 v3, 32, v3
	v_or_b32_e32 v2, v0, v1
	v_bitop3_b32 v0, v0, v3, v1 bitop3:0x36
	v_or_b32_e32 v5, s10, v0
	v_lshlrev_b32_e32 v0, 13, v13
	v_and_b32_e32 v0, 0xffffc000, v0
	v_lshl_add_u32 v0, v14, 10, v0
	v_or_b32_e32 v0, v0, v15
	v_add_u32_sdwa v0, v0, sext(v17) dst_sel:DWORD dst_unused:UNUSED_PAD src0_sel:DWORD src1_sel:WORD_0
	v_bitop3_b32 v4, v2, s7, v3 bitop3:0xde
	v_ashrrev_i32_e32 v1, 31, v0
	v_mov_b64_e32 v[2:3], 0x40080
	v_lshl_add_u64 v[132:133], v[0:1], 1, v[2:3]
	v_lshlrev_b32_e32 v0, 13, v16
	v_and_b32_e32 v0, 0xffffc000, v0
	s_ashr_i32 s60, s28, 31
	s_ashr_i32 s62, s2, 31
	s_ashr_i32 s63, s2, 3
	s_ashr_i32 s64, s28, 3
	s_and_b32 s65, s2, 7
	v_lshl_add_u32 v0, v18, 10, v0
	s_cmpk_lt_u32 s6, 0x100
	v_or_b32_e32 v0, v0, v19
	s_cselect_b64 s[6:7], -1, 0
	s_add_u32 s8, s26, 0x1e720000
	v_add_u32_sdwa v0, v0, sext(v20) dst_sel:DWORD dst_unused:UNUSED_PAD src0_sel:DWORD src1_sel:WORD_0
	s_waitcnt vmcnt(6)
	s_addc_u32 s9, s27, 0
	v_ashrrev_i32_e32 v1, 31, v0
	s_add_u32 s66, s26, 0x6300000
	v_lshl_add_u64 v[134:135], v[0:1], 1, v[2:3]
	v_add_u32_e32 v0, 0, v5
	s_mov_b32 s61, s28
	s_addc_u32 s67, s27, 0
	v_add_u32_e32 v141, 0x10000, v0
	v_add_u32_e32 v143, 0x14000, v0
	v_add_u32_e32 v145, 0, v4
	s_add_i32 s68, s3, 0xc000
	s_add_i32 s69, s3, 0xe000
	v_add_u32_e32 v149, 0x18000, v0
	v_add_u32_e32 v150, 0x1c000, v0
	v_mov_b32_e32 v151, 0x358637bd
	v_mov_b32_e32 v137, 0
	s_movk_i32 s70, 0x1600
	s_mov_b32 s71, 0x2c000
	s_mov_b32 s72, 0x42000
	s_mov_b32 s73, 0xb0000
	s_mov_b32 s74, 0xc6000
	s_mov_b32 s75, 0xdc000
	v_mov_b64_e32 v[138:139], 0xaff
	s_barrier
	s_branch .LBB0_1049

.LBB0_1129:
	s_lshl_b32 s4, s4, 12
	s_lshl_b32 s7, s5, 13
	s_and_b32 s9, s4, 0x3000
	s_mov_b64 s[4:5], 0x80
	s_add_i32 s45, s3, 0x18000
	v_lshl_add_u64 v[4:5], v[4:5], 0, s[4:5]
	s_mov_b32 m0, s45
	s_add_i32 s46, s3, 0x1a000
	s_barrier
	global_load_lds_dwordx4 v[4:5], off
	v_lshl_add_u64 v[4:5], v[6:7], 0, s[4:5]
	s_mov_b32 m0, s46
	s_add_i32 s47, s3, 0x8000
	s_add_i32 s48, s3, 0xa000
	global_load_lds_dwordx4 v[4:5], off
	v_lshl_add_u64 v[4:5], v[10:11], 0, s[4:5]
	s_mov_b32 m0, s47
	s_add_u32 s10, s18, 0xb0080
	global_load_lds_dwordx4 v[4:5], off
	v_lshl_add_u64 v[4:5], v[8:9], 0, s[4:5]
	s_mov_b32 m0, s48
	s_addc_u32 s11, s19, 0
	s_add_i32 s49, s3, 0x1c000
	global_load_lds_dwordx4 v[4:5], off
	v_lshl_add_u64 v[2:3], v[2:3], 1, s[10:11]
	s_mov_b32 m0, s49
	s_add_i32 s50, s3, 0x1e000
	global_load_lds_dwordx4 v[2:3], off
	v_lshl_add_u64 v[0:1], v[0:1], 1, s[10:11]
	s_mov_b32 m0, s50
	v_lshlrev_b32_e32 v3, 2, v12
	global_load_lds_dwordx4 v[0:1], off
	v_and_b32_e32 v0, 15, v12
	v_and_b32_e32 v1, 48, v12
	v_lshlrev_b32_e32 v0, 6, v0
	v_and_b32_e32 v3, 32, v3
	v_or_b32_e32 v2, v0, v1
	v_bitop3_b32 v0, v0, v3, v1 bitop3:0x36
	v_or_b32_e32 v5, s9, v0
	v_lshrrev_b32_e32 v1, 1, v13
	v_mul_lo_u32 v0, v15, s8
	s_mov_b32 s9, 0xb000
	v_mad_u64_u32 v[0:1], s[10:11], v1, s9, v[0:1]
	v_or_b32_e32 v0, v0, v14
	v_add_u32_sdwa v0, v0, sext(v17) dst_sel:DWORD dst_unused:UNUSED_PAD src0_sel:DWORD src1_sel:WORD_0
	v_bitop3_b32 v4, v2, s7, v3 bitop3:0xde
	v_ashrrev_i32_e32 v1, 31, v0
	v_mov_b64_e32 v[2:3], 0xb0080
	v_lshl_add_u64 v[132:133], v[0:1], 1, v[2:3]
	v_lshrrev_b32_e32 v1, 1, v16
	v_mul_lo_u32 v0, v18, s8
	v_mad_u64_u32 v[0:1], s[8:9], v1, s9, v[0:1]
	v_or_b32_e32 v0, v0, v19
	v_add_u32_sdwa v0, v0, sext(v20) dst_sel:DWORD dst_unused:UNUSED_PAD src0_sel:DWORD src1_sel:WORD_0
	s_waitcnt vmcnt(6)
	s_ashr_i32 s51, s28, 31
	s_ashr_i32 s52, s2, 31
	s_ashr_i32 s53, s2, 3
	s_ashr_i32 s54, s28, 3
	s_and_b32 s55, s2, 7
	v_ashrrev_i32_e32 v1, 31, v0
	s_cmpk_lt_u32 s6, 0x100
	v_lshl_add_u64 v[134:135], v[0:1], 1, v[2:3]
	v_add_u32_e32 v0, 0, v5
	s_cselect_b64 s[6:7], -1, 0
	v_add_u32_e32 v140, 0x10000, v0
	v_add_u32_e32 v141, 0x14000, v0
	v_add_u32_e32 v142, 0, v4
	s_add_i32 s56, s3, 0xc000
	s_add_i32 s57, s3, 0xe000
	v_add_u32_e32 v143, 0x18000, v0
	v_add_u32_e32 v144, 0x1c000, v0
	v_mov_b32_e32 v137, 0
	s_mov_b32 s58, 0x20000
	s_mov_b32 s59, 0x30000
	s_mov_b32 s60, 0x80000
	s_mov_b32 s61, 0x90000
	s_mov_b32 s62, 0xa0000
	s_mov_b32 s63, 0xb0000
	v_mov_b64_e32 v[138:139], 0x1ff
	s_barrier
	s_branch .LBB0_1132
